# attention units: next unit's Q/K/V loads issued before the current unit's epilogue (software-pipelined unit transition)
# speedup vs baseline: 1.0090x; 1.0046x over previous
.Lat_g1:
	s_cmp_lg_u64 s[90:91], 0
	s_cselect_b32 s1, 0, s1
	s_mov_b32 s100, s1
	s_add_i32 s7, s6, s1
	v_and_b32_e32 v32, 31, v143
	v_bfe_u32 v33, v143, 5, 1
	v_lshrrev_b32_e32 v34, 6, v143
	v_and_b32_e32 v35, 3, v143
	v_lshlrev_b32_e32 v238, 3, v35
	v_bfe_u32 v35, v143, 2, 2
	v_lshl_add_u32 v238, v35, 6, v238
	v_bfe_u32 v35, v143, 4, 1
	v_lshl_add_u32 v238, v35, 5, v238
	v_lshl_add_u32 v238, v33, 8, v238
	v_lshlrev_b32_e32 v232, 4, v143
	v_add_u32_e32 v239, 0x2000, v232
	v_add_u32_e32 v252, 0x4000, v232
	v_lshlrev_b32_e32 v183, 10, v34
	v_bfe_u32 v35, v143, 2, 1
	v_lshl_add_u32 v183, v35, 9, v183
	v_bfe_u32 v35, v143, 3, 3
	v_lshl_add_u32 v183, v35, 6, v183
	v_and_b32_e32 v35, 3, v143
	v_lshl_add_u32 v183, v35, 4, v183
	v_lshl_add_u32 v39, v34, 5, v32
	v_mul_u32_u24_e32 v133, 0x1440, v39
	v_lshl_add_u32 v133, v33, 3, v133
	v_lshlrev_b32_e32 v134, 11, v39
	v_lshl_add_u32 v134, v33, 3, v134
	s_mov_b32 s101, 0
	s_cmp_ge_i32 s4, s7
	s_cbranch_scc1 .Lat_de_end
	s_cmp_ge_i32 s4, s6
	s_cbranch_scc1 .Lat_de_ctx
	s_mul_i32 s0, s8, s6
	s_add_i32 s0, s0, s4
	s_mul_hi_u32 s1, s0, 0xaaaaaaab
	s_lshr_b32 s1, s1, 7
	s_mul_i32 s32, s1, 192
	s_sub_i32 s32, s0, s32
	s_lshr_b32 s56, s32, 4
	s_and_b32 s32, s32, 15
	s_lshl_b32 s76, s32, 8
	s_lshl_b32 s77, s1, 12
	s_add_i32 s77, s77, s76
	s_mov_b32 s78, 0
	s_mov_b32 s27, 32
	s_branch .Lat_de_ptrs

.Lat_m_pref:
	v_and_b32_e32 v32, 31, v143
	v_bfe_u32 v33, v143, 5, 1
	v_mul_u32_u24_e32 v237, 208, v32
	v_lshl_add_u32 v237, v33, 4, v237
	v_mov_b32_e32 v36, v143
	v_mul_u32_u24_e32 v37, 0xaaab, v36
	v_lshrrev_b32_e32 v37, 19, v37
	v_mul_u32_u24_e32 v38, 12, v37
	v_sub_u32_e32 v38, v36, v38
	v_mul_u32_u24_e32 v37, 208, v37
	v_lshl_add_u32 v179, v38, 4, v37
	v_add_u32_e32 v36, 512, v143
	v_mul_u32_u24_e32 v37, 0xaaab, v36
	v_lshrrev_b32_e32 v37, 19, v37
	v_mul_u32_u24_e32 v38, 12, v37
	v_sub_u32_e32 v38, v36, v38
	v_mul_u32_u24_e32 v37, 208, v37
	v_lshl_add_u32 v181, v38, 4, v37
	v_add_u32_e32 v36, 1024, v143
	v_mul_u32_u24_e32 v37, 0xaaab, v36
	v_lshrrev_b32_e32 v37, 19, v37
	v_mul_u32_u24_e32 v38, 12, v37
	v_sub_u32_e32 v38, v36, v38
	v_mul_u32_u24_e32 v37, 208, v37
	v_lshl_add_u32 v182, v38, 4, v37
	s_mov_b32 s64, 0
	s_movk_i32 s65, 26624
	s_mov_b32 s68, 53248
	s_mov_b32 s69, 112640
	s_mov_b32 s70, 79872
	s_mov_b32 s71, 96256
	v_mov_b32_e32 v130, 0
	v_mov_b32_e32 v131, 0
	v_mov_b32_e32 v0, 0
	v_mov_b32_e32 v1, 0
	v_mov_b32_e32 v2, 0
	v_mov_b32_e32 v3, 0
	v_mov_b32_e32 v4, 0
	v_mov_b32_e32 v5, 0
	v_mov_b32_e32 v6, 0
	v_mov_b32_e32 v7, 0
	v_mov_b32_e32 v8, 0
	v_mov_b32_e32 v9, 0
	v_mov_b32_e32 v10, 0
	v_mov_b32_e32 v11, 0
	v_mov_b32_e32 v12, 0
	v_mov_b32_e32 v13, 0
	v_mov_b32_e32 v14, 0
	v_mov_b32_e32 v15, 0
	v_mov_b32_e32 v16, 0
	v_mov_b32_e32 v17, 0
	v_mov_b32_e32 v18, 0
	v_mov_b32_e32 v19, 0
	v_mov_b32_e32 v20, 0
	v_mov_b32_e32 v21, 0
	v_mov_b32_e32 v22, 0
	v_mov_b32_e32 v23, 0
	v_mov_b32_e32 v24, 0
	v_mov_b32_e32 v25, 0
	v_mov_b32_e32 v26, 0
	v_mov_b32_e32 v27, 0
	v_mov_b32_e32 v28, 0
	v_mov_b32_e32 v29, 0
	v_mov_b32_e32 v30, 0
	v_mov_b32_e32 v31, 0
	s_waitcnt vmcnt(11)
	ds_write_b128 v179, v[208:211]
	ds_write_b128 v181, v[212:215]
	ds_write_b128 v182, v[216:219]
	v_add_u32_e32 v128, 79872, v183
	ds_write_b128 v128, v[220:223]
	ds_write_b128 v128, v[224:227] offset:8192
	global_load_dwordx4 v[208:211], v232, s[16:17]
	global_load_dwordx4 v[212:215], v239, s[16:17]
	global_load_dwordx4 v[216:219], v252, s[16:17]
	global_load_dwordx4 v[220:223], v232, s[22:23]
	global_load_dwordx4 v[224:227], v239, s[22:23]
	s_add_u32 s16, s16, 24576
	s_addc_u32 s17, s17, 0
	s_add_u32 s22, s22, 16384
	s_addc_u32 s23, s23, 0
	s_waitcnt vmcnt(13)
	v_add_u32_e32 v128, 26624, v179
	ds_write_b128 v128, v[144:147]
	v_add_u32_e32 v128, 26624, v181
	ds_write_b128 v128, v[148:151]
	v_add_u32_e32 v128, 26624, v182
	ds_write_b128 v128, v[152:155]
	v_add_u32_e32 v140, s64, v237
	s_waitcnt lgkmcnt(0)
	s_barrier
	s_branch .Lat_m_body
.Lat_m_first:
	v_and_b32_e32 v32, 31, v143
	v_bfe_u32 v33, v143, 5, 1
	v_mul_u32_u24_e32 v237, 208, v32
	v_lshl_add_u32 v237, v33, 4, v237
	v_mov_b32_e32 v36, v143
	v_mul_u32_u24_e32 v37, 0xaaab, v36
	v_lshrrev_b32_e32 v37, 19, v37
	v_mul_u32_u24_e32 v38, 12, v37
	v_sub_u32_e32 v38, v36, v38
	v_mul_u32_u24_e32 v37, 208, v37
	v_lshl_add_u32 v179, v38, 4, v37
	v_add_u32_e32 v36, 512, v143
	v_mul_u32_u24_e32 v37, 0xaaab, v36
	v_lshrrev_b32_e32 v37, 19, v37
	v_mul_u32_u24_e32 v38, 12, v37
	v_sub_u32_e32 v38, v36, v38
	v_mul_u32_u24_e32 v37, 208, v37
	v_lshl_add_u32 v181, v38, 4, v37
	v_add_u32_e32 v36, 1024, v143
	v_mul_u32_u24_e32 v37, 0xaaab, v36
	v_lshrrev_b32_e32 v37, 19, v37
	v_mul_u32_u24_e32 v38, 12, v37
	v_sub_u32_e32 v38, v36, v38
	v_mul_u32_u24_e32 v37, 208, v37
	v_lshl_add_u32 v182, v38, 4, v37
	s_mov_b32 s64, 0
	s_movk_i32 s65, 26624
	s_mov_b32 s68, 53248
	s_mov_b32 s69, 112640
	s_mov_b32 s70, 79872
	s_mov_b32 s71, 96256
	v_mov_b32_e32 v130, 0
	v_mov_b32_e32 v131, 0
	v_mov_b32_e32 v0, 0
	v_mov_b32_e32 v1, 0
	v_mov_b32_e32 v2, 0
	v_mov_b32_e32 v3, 0
	v_mov_b32_e32 v4, 0
	v_mov_b32_e32 v5, 0
	v_mov_b32_e32 v6, 0
	v_mov_b32_e32 v7, 0
	v_mov_b32_e32 v8, 0
	v_mov_b32_e32 v9, 0
	v_mov_b32_e32 v10, 0
	v_mov_b32_e32 v11, 0
	v_mov_b32_e32 v12, 0
	v_mov_b32_e32 v13, 0
	v_mov_b32_e32 v14, 0
	v_mov_b32_e32 v15, 0
	v_mov_b32_e32 v16, 0
	v_mov_b32_e32 v17, 0
	v_mov_b32_e32 v18, 0
	v_mov_b32_e32 v19, 0
	v_mov_b32_e32 v20, 0
	v_mov_b32_e32 v21, 0
	v_mov_b32_e32 v22, 0
	v_mov_b32_e32 v23, 0
	v_mov_b32_e32 v24, 0
	v_mov_b32_e32 v25, 0
	v_mov_b32_e32 v26, 0
	v_mov_b32_e32 v27, 0
	v_mov_b32_e32 v28, 0
	v_mov_b32_e32 v29, 0
	v_mov_b32_e32 v30, 0
	v_mov_b32_e32 v31, 0
	s_waitcnt vmcnt(3)
	ds_write_b128 v179, v[208:211]
	ds_write_b128 v181, v[212:215]
	ds_write_b128 v182, v[216:219]
	v_add_u32_e32 v128, 79872, v183
	ds_write_b128 v128, v[220:223]
	ds_write_b128 v128, v[224:227] offset:8192
	global_load_dwordx4 v[208:211], v232, s[16:17]
	global_load_dwordx4 v[212:215], v239, s[16:17]
	global_load_dwordx4 v[216:219], v252, s[16:17]
	global_load_dwordx4 v[220:223], v232, s[22:23]
	global_load_dwordx4 v[224:227], v239, s[22:23]
	s_add_u32 s16, s16, 24576
	s_addc_u32 s17, s17, 0
	s_add_u32 s22, s22, 16384
	s_addc_u32 s23, s23, 0
	s_waitcnt vmcnt(5)
	v_add_u32_e32 v128, 26624, v179
	ds_write_b128 v128, v[144:147]
	v_add_u32_e32 v128, 26624, v181
	ds_write_b128 v128, v[148:151]
	v_add_u32_e32 v128, 26624, v182
	ds_write_b128 v128, v[152:155]
	v_add_u32_e32 v140, s64, v237
	s_waitcnt lgkmcnt(0)
	s_barrier

.Lat_m_last:
	v_add_u32_e32 v140, s64, v237
	v_add_u32_e32 v141, s65, v237
	v_add_u32_e32 v176, s69, v238
	v_add_u32_e32 v177, s70, v238
	s_waitcnt lgkmcnt(5)
	v_mfma_f32_32x32x16_bf16 v[64:79], v[160:163], v[184:187], 0
	ds_read_b128 v[152:155], v140 offset:19968
	v_exp_f32_e32 v32, v32
	v_exp_f32_e32 v33, v33
	v_add_f32_e32 v130, v130, v32
	v_add_f32_e32 v131, v131, v33
	s_waitcnt lgkmcnt(5)
	v_mfma_f32_32x32x16_bf16 v[64:79], v[164:167], v[188:191], v[64:79]
	ds_read_b128 v[156:159], v140 offset:20000
	v_cvt_pk_bf16_f32 v96, v32, v33
	v_exp_f32_e32 v34, v34
	v_exp_f32_e32 v35, v35
	v_add_f32_e32 v130, v130, v34
	s_waitcnt lgkmcnt(5)
	v_mfma_f32_32x32x16_bf16 v[64:79], v[168:171], v[192:195], v[64:79]
	ds_read_b128 v[160:163], v140 offset:20032
	v_add_f32_e32 v131, v131, v35
	v_cvt_pk_bf16_f32 v97, v34, v35
	v_exp_f32_e32 v36, v36
	v_exp_f32_e32 v37, v37
	s_waitcnt lgkmcnt(5)
	v_mfma_f32_32x32x16_bf16 v[64:79], v[172:175], v[196:199], v[64:79]
	ds_read_b128 v[164:167], v140 offset:20064
	v_add_f32_e32 v130, v130, v36
	v_add_f32_e32 v131, v131, v37
	v_cvt_pk_bf16_f32 v98, v36, v37
	v_exp_f32_e32 v38, v38
	s_waitcnt lgkmcnt(5)
	v_mfma_f32_32x32x16_bf16 v[64:79], v[144:147], v[200:203], v[64:79]
	ds_read_b128 v[168:171], v140 offset:20096
	v_exp_f32_e32 v39, v39
	v_add_f32_e32 v130, v130, v38
	v_add_f32_e32 v131, v131, v39
	v_cvt_pk_bf16_f32 v99, v38, v39
	s_waitcnt lgkmcnt(5)
	v_mfma_f32_32x32x16_bf16 v[64:79], v[148:151], v[204:207], v[64:79]
	ds_read_b128 v[172:175], v140 offset:20128
	v_exp_f32_e32 v40, v40
	v_exp_f32_e32 v41, v41
	v_add_f32_e32 v130, v130, v40
	v_add_f32_e32 v131, v131, v41
	s_waitcnt lgkmcnt(5)
	v_mfma_f32_32x32x16_bf16 v[80:95], v[152:155], v[184:187], 0
	ds_read_b64_tr_b16 v[144:145], v176 offset:8192
	ds_read_b64_tr_b16 v[146:147], v176 offset:9216
	v_cvt_pk_bf16_f32 v100, v40, v41
	v_exp_f32_e32 v42, v42
	v_exp_f32_e32 v43, v43
	v_add_f32_e32 v130, v130, v42
	s_waitcnt lgkmcnt(6)
	v_mfma_f32_32x32x16_bf16 v[80:95], v[156:159], v[188:191], v[80:95]
	ds_read_b64_tr_b16 v[148:149], v176 offset:8704
	ds_read_b64_tr_b16 v[150:151], v176 offset:9728
	v_add_f32_e32 v131, v131, v43
	v_cvt_pk_bf16_f32 v101, v42, v43
	v_exp_f32_e32 v44, v44
	v_exp_f32_e32 v45, v45
	s_waitcnt lgkmcnt(7)
	v_mfma_f32_32x32x16_bf16 v[80:95], v[160:163], v[192:195], v[80:95]
	ds_read_b64_tr_b16 v[152:153], v176 offset:10240
	ds_read_b64_tr_b16 v[154:155], v176 offset:11264
	v_add_f32_e32 v130, v130, v44
	v_add_f32_e32 v131, v131, v45
	v_cvt_pk_bf16_f32 v102, v44, v45
	v_exp_f32_e32 v46, v46
	s_waitcnt lgkmcnt(8)
	v_mfma_f32_32x32x16_bf16 v[80:95], v[164:167], v[196:199], v[80:95]
	ds_read_b64_tr_b16 v[156:157], v176 offset:10752
	ds_read_b64_tr_b16 v[158:159], v176 offset:11776
	v_exp_f32_e32 v47, v47
	v_add_f32_e32 v130, v130, v46
	v_add_f32_e32 v131, v131, v47
	v_cvt_pk_bf16_f32 v103, v46, v47
	s_waitcnt lgkmcnt(9)
	v_mfma_f32_32x32x16_bf16 v[80:95], v[168:171], v[200:203], v[80:95]
	ds_read_b64_tr_b16 v[160:161], v176 offset:12288
	ds_read_b64_tr_b16 v[162:163], v176 offset:13312
	v_exp_f32_e32 v48, v48
	v_exp_f32_e32 v49, v49
	v_add_f32_e32 v130, v130, v48
	v_add_f32_e32 v131, v131, v49
	s_waitcnt lgkmcnt(10)
	v_mfma_f32_32x32x16_bf16 v[80:95], v[172:175], v[204:207], v[80:95]
	ds_read_b64_tr_b16 v[164:165], v176 offset:12800
	ds_read_b64_tr_b16 v[166:167], v176 offset:13824
	v_cvt_pk_bf16_f32 v104, v48, v49
	v_exp_f32_e32 v50, v50
	v_exp_f32_e32 v51, v51
	v_add_f32_e32 v130, v130, v50
	s_waitcnt lgkmcnt(10)
	v_mfma_f32_32x32x16_bf16 v[0:15], v[144:147], v[112:115], v[0:15]
	ds_read_b64_tr_b16 v[168:169], v176 offset:14336
	ds_read_b64_tr_b16 v[170:171], v176 offset:15360
	v_add_f32_e32 v131, v131, v51
	v_cvt_pk_bf16_f32 v105, v50, v51
	v_exp_f32_e32 v52, v52
	v_exp_f32_e32 v53, v53
	s_waitcnt lgkmcnt(10)
	v_mfma_f32_32x32x16_bf16 v[16:31], v[148:151], v[112:115], v[16:31]
	ds_read_b64_tr_b16 v[172:173], v176 offset:14848
	ds_read_b64_tr_b16 v[174:175], v176 offset:15872
	v_add_f32_e32 v130, v130, v52
	v_add_f32_e32 v131, v131, v53
	v_cvt_pk_bf16_f32 v106, v52, v53
	v_exp_f32_e32 v54, v54
	s_waitcnt lgkmcnt(10)
	v_mfma_f32_32x32x16_bf16 v[0:15], v[152:155], v[116:119], v[0:15]
	ds_read_b64_tr_b16 v[144:145], v177 offset:0
	ds_read_b64_tr_b16 v[146:147], v177 offset:1024
	v_exp_f32_e32 v55, v55
	v_add_f32_e32 v130, v130, v54
	v_add_f32_e32 v131, v131, v55
	v_cvt_pk_bf16_f32 v107, v54, v55
	s_waitcnt lgkmcnt(10)
	v_mfma_f32_32x32x16_bf16 v[16:31], v[156:159], v[116:119], v[16:31]
	ds_read_b64_tr_b16 v[148:149], v177 offset:512
	ds_read_b64_tr_b16 v[150:151], v177 offset:1536
	v_exp_f32_e32 v56, v56
	v_exp_f32_e32 v57, v57
	v_add_f32_e32 v130, v130, v56
	v_add_f32_e32 v131, v131, v57
	s_waitcnt lgkmcnt(10)
	v_mfma_f32_32x32x16_bf16 v[0:15], v[160:163], v[120:123], v[0:15]
	ds_read_b64_tr_b16 v[152:153], v177 offset:2048
	ds_read_b64_tr_b16 v[154:155], v177 offset:3072
	v_cvt_pk_bf16_f32 v108, v56, v57
	v_exp_f32_e32 v58, v58
	v_exp_f32_e32 v59, v59
	v_add_f32_e32 v130, v130, v58
	s_waitcnt lgkmcnt(10)
	v_mfma_f32_32x32x16_bf16 v[16:31], v[164:167], v[120:123], v[16:31]
	ds_read_b64_tr_b16 v[156:157], v177 offset:2560
	ds_read_b64_tr_b16 v[158:159], v177 offset:3584
	v_add_f32_e32 v131, v131, v59
	v_cvt_pk_bf16_f32 v109, v58, v59
	v_exp_f32_e32 v60, v60
	v_exp_f32_e32 v61, v61
	s_waitcnt lgkmcnt(10)
	v_mfma_f32_32x32x16_bf16 v[0:15], v[168:171], v[124:127], v[0:15]
	ds_read_b64_tr_b16 v[160:161], v177 offset:4096
	ds_read_b64_tr_b16 v[162:163], v177 offset:5120
	v_add_f32_e32 v130, v130, v60
	v_add_f32_e32 v131, v131, v61
	v_cvt_pk_bf16_f32 v110, v60, v61
	v_exp_f32_e32 v62, v62
	s_waitcnt lgkmcnt(10)
	v_mfma_f32_32x32x16_bf16 v[16:31], v[172:175], v[124:127], v[16:31]
	ds_read_b64_tr_b16 v[164:165], v177 offset:4608
	ds_read_b64_tr_b16 v[166:167], v177 offset:5632
	v_exp_f32_e32 v63, v63
	v_add_f32_e32 v130, v130, v62
	v_add_f32_e32 v131, v131, v63
	v_cvt_pk_bf16_f32 v111, v62, v63
	s_waitcnt lgkmcnt(10)
	v_mfma_f32_32x32x16_bf16 v[0:15], v[144:147], v[96:99], v[0:15]
	ds_read_b64_tr_b16 v[168:169], v177 offset:6144
	ds_read_b64_tr_b16 v[170:171], v177 offset:7168
	v_exp_f32_e32 v64, v64
	v_exp_f32_e32 v65, v65
	v_add_f32_e32 v130, v130, v64
	v_add_f32_e32 v131, v131, v65
	v_cvt_pk_bf16_f32 v112, v64, v65
	v_exp_f32_e32 v66, v66
	v_exp_f32_e32 v67, v67
	v_add_f32_e32 v130, v130, v66
	v_add_f32_e32 v131, v131, v67
	v_cvt_pk_bf16_f32 v113, v66, v67
	global_load_dwordx2 v[32:33], v133, s[12:13] offset:0
	s_waitcnt lgkmcnt(10)
	v_mfma_f32_32x32x16_bf16 v[16:31], v[148:151], v[96:99], v[16:31]
	ds_read_b64_tr_b16 v[172:173], v177 offset:6656
	ds_read_b64_tr_b16 v[174:175], v177 offset:7680
	v_exp_f32_e32 v68, v68
	v_exp_f32_e32 v69, v69
	v_add_f32_e32 v130, v130, v68
	v_add_f32_e32 v131, v131, v69
	v_cvt_pk_bf16_f32 v114, v68, v69
	v_exp_f32_e32 v70, v70
	v_exp_f32_e32 v71, v71
	v_add_f32_e32 v130, v130, v70
	v_add_f32_e32 v131, v131, v71
	v_cvt_pk_bf16_f32 v115, v70, v71
	global_load_dwordx2 v[34:35], v133, s[12:13] offset:64
	s_waitcnt lgkmcnt(10)
	v_mfma_f32_32x32x16_bf16 v[0:15], v[152:155], v[100:103], v[0:15]
	v_exp_f32_e32 v72, v72
	v_exp_f32_e32 v73, v73
	v_add_f32_e32 v130, v130, v72
	v_add_f32_e32 v131, v131, v73
	v_cvt_pk_bf16_f32 v116, v72, v73
	v_exp_f32_e32 v74, v74
	v_exp_f32_e32 v75, v75
	v_add_f32_e32 v130, v130, v74
	v_add_f32_e32 v131, v131, v75
	v_cvt_pk_bf16_f32 v117, v74, v75
	global_load_dwordx2 v[36:37], v133, s[12:13] offset:16
	s_waitcnt lgkmcnt(8)
	v_mfma_f32_32x32x16_bf16 v[16:31], v[156:159], v[100:103], v[16:31]
	v_exp_f32_e32 v76, v76
	v_exp_f32_e32 v77, v77
	v_add_f32_e32 v130, v130, v76
	v_add_f32_e32 v131, v131, v77
	v_cvt_pk_bf16_f32 v118, v76, v77
	v_exp_f32_e32 v78, v78
	v_exp_f32_e32 v79, v79
	v_add_f32_e32 v130, v130, v78
	v_add_f32_e32 v131, v131, v79
	v_cvt_pk_bf16_f32 v119, v78, v79
	global_load_dwordx2 v[38:39], v133, s[12:13] offset:80
	s_waitcnt lgkmcnt(6)
	v_mfma_f32_32x32x16_bf16 v[0:15], v[160:163], v[104:107], v[0:15]
	v_exp_f32_e32 v80, v80
	v_exp_f32_e32 v81, v81
	v_add_f32_e32 v130, v130, v80
	v_add_f32_e32 v131, v131, v81
	v_cvt_pk_bf16_f32 v120, v80, v81
	v_exp_f32_e32 v82, v82
	v_exp_f32_e32 v83, v83
	v_add_f32_e32 v130, v130, v82
	v_add_f32_e32 v131, v131, v83
	v_cvt_pk_bf16_f32 v121, v82, v83
	global_load_dwordx2 v[40:41], v133, s[12:13] offset:32
	s_waitcnt lgkmcnt(4)
	v_mfma_f32_32x32x16_bf16 v[16:31], v[164:167], v[104:107], v[16:31]
	v_exp_f32_e32 v84, v84
	v_exp_f32_e32 v85, v85
	v_add_f32_e32 v130, v130, v84
	v_add_f32_e32 v131, v131, v85
	v_cvt_pk_bf16_f32 v122, v84, v85
	v_exp_f32_e32 v86, v86
	v_exp_f32_e32 v87, v87
	v_add_f32_e32 v130, v130, v86
	v_add_f32_e32 v131, v131, v87
	v_cvt_pk_bf16_f32 v123, v86, v87
	global_load_dwordx2 v[42:43], v133, s[12:13] offset:96
	s_waitcnt lgkmcnt(2)
	v_mfma_f32_32x32x16_bf16 v[0:15], v[168:171], v[108:111], v[0:15]
	v_exp_f32_e32 v88, v88
	v_exp_f32_e32 v89, v89
	v_add_f32_e32 v130, v130, v88
	v_add_f32_e32 v131, v131, v89
	v_cvt_pk_bf16_f32 v124, v88, v89
	v_exp_f32_e32 v90, v90
	v_exp_f32_e32 v91, v91
	v_add_f32_e32 v130, v130, v90
	v_add_f32_e32 v131, v131, v91
	v_cvt_pk_bf16_f32 v125, v90, v91
	global_load_dwordx2 v[44:45], v133, s[12:13] offset:48
	s_waitcnt lgkmcnt(0)
	v_mfma_f32_32x32x16_bf16 v[16:31], v[172:175], v[108:111], v[16:31]
	v_exp_f32_e32 v92, v92
	v_exp_f32_e32 v93, v93
	v_add_f32_e32 v130, v130, v92
	v_add_f32_e32 v131, v131, v93
	v_cvt_pk_bf16_f32 v126, v92, v93
	v_exp_f32_e32 v94, v94
	v_exp_f32_e32 v95, v95
	v_add_f32_e32 v130, v130, v94
	v_add_f32_e32 v131, v131, v95
	v_cvt_pk_bf16_f32 v127, v94, v95
	global_load_dwordx2 v[46:47], v133, s[12:13] offset:112
	v_add_u32_e32 v176, s70, v238
	ds_read_b64_tr_b16 v[144:145], v176 offset:8192
	ds_read_b64_tr_b16 v[146:147], v176 offset:9216
	ds_read_b64_tr_b16 v[148:149], v176 offset:8704
	ds_read_b64_tr_b16 v[150:151], v176 offset:9728
	ds_read_b64_tr_b16 v[152:153], v176 offset:10240
	ds_read_b64_tr_b16 v[154:155], v176 offset:11264
	ds_read_b64_tr_b16 v[156:157], v176 offset:10752
	ds_read_b64_tr_b16 v[158:159], v176 offset:11776
	ds_read_b64_tr_b16 v[160:161], v176 offset:12288
	ds_read_b64_tr_b16 v[162:163], v176 offset:13312
	ds_read_b64_tr_b16 v[164:165], v176 offset:12800
	ds_read_b64_tr_b16 v[166:167], v176 offset:13824
	s_waitcnt lgkmcnt(10)
	v_mfma_f32_32x32x16_bf16 v[0:15], v[144:147], v[112:115], v[0:15]
	ds_read_b64_tr_b16 v[168:169], v176 offset:14336
	ds_read_b64_tr_b16 v[170:171], v176 offset:15360
	s_waitcnt lgkmcnt(10)
	v_mfma_f32_32x32x16_bf16 v[16:31], v[148:151], v[112:115], v[16:31]
	ds_read_b64_tr_b16 v[172:173], v176 offset:14848
	ds_read_b64_tr_b16 v[174:175], v176 offset:15872
	s_waitcnt lgkmcnt(10)
	v_mfma_f32_32x32x16_bf16 v[0:15], v[152:155], v[116:119], v[0:15]
	s_waitcnt lgkmcnt(8)
	v_mfma_f32_32x32x16_bf16 v[16:31], v[156:159], v[116:119], v[16:31]
	s_waitcnt lgkmcnt(6)
	v_mfma_f32_32x32x16_bf16 v[0:15], v[160:163], v[120:123], v[0:15]
	s_waitcnt lgkmcnt(4)
	v_mfma_f32_32x32x16_bf16 v[16:31], v[164:167], v[120:123], v[16:31]
	s_waitcnt lgkmcnt(2)
	v_mfma_f32_32x32x16_bf16 v[0:15], v[168:171], v[124:127], v[0:15]
	s_waitcnt lgkmcnt(0)
	v_mfma_f32_32x32x16_bf16 v[16:31], v[172:175], v[124:127], v[16:31]
	s_waitcnt vmcnt(0)
	s_mov_b64 s[30:31], s[14:15]
	s_add_i32 s4, s4, s5
	s_mov_b32 s101, 0
	s_cmp_ge_i32 s4, s7
	s_cbranch_scc1 .Lat_dm_end
	s_cmp_ge_i32 s4, s6
	s_cbranch_scc1 .Lat_dm_ctx
	s_mul_i32 s0, s8, s6
	s_add_i32 s0, s0, s4
	s_mul_hi_u32 s1, s0, 0xaaaaaaab
	s_lshr_b32 s1, s1, 7
	s_mul_i32 s32, s1, 192
	s_sub_i32 s32, s0, s32
	s_lshr_b32 s56, s32, 4
	s_and_b32 s32, s32, 15
	s_lshl_b32 s76, s32, 8
	s_lshl_b32 s77, s1, 12
	s_add_i32 s77, s77, s76
	s_mov_b32 s78, 0
	s_mov_b32 s27, 32
	s_branch .Lat_dm_ptrs

.Lat_dm_end:
	v_add_f32_e32 v135, v130, v131
	v_mov_b32_e32 v128, v135
	s_nop 1
	v_permlane32_swap_b32_e32 v135, v128
	s_nop 1
	v_add_f32_e32 v135, v135, v128
	s_mov_b32 s0, 0x7149f2ca
	v_cmp_lt_f32_e32 vcc, 0xda24260, v135
	v_cmp_gt_f32_e64 s[76:77], s0, v135
	s_nop 1
	s_and_b64 s[76:77], s[76:77], vcc
	s_andn2_b64 s[76:77], exec, s[76:77]
	s_cmp_lg_u64 s[76:77], 0
	s_cselect_b32 s0, 1, 0
	v_mov_b32_e32 v128, s0
	v_lshrrev_b32_e32 v132, 6, v143
	v_lshlrev_b32_e32 v132, 2, v132
	v_add_u32_e32 v132, 131072, v132
	ds_write_b32 v132, v128
	s_waitcnt lgkmcnt(0)
	s_barrier
	v_mov_b32_e32 v132, 131072
	ds_read_b128 v[48:51], v132
	ds_read_b128 v[52:55], v132 offset:16
	v_rcp_f32_e32 v136, v135
	s_nop 0
	v_fma_f32 v128, -v135, v136, 1.0
	v_fma_f32 v136, v136, v128, v136
	s_waitcnt lgkmcnt(0)
	v_or_b32_e32 v48, v48, v49
	v_or3_b32 v48, v48, v50, v51
	v_or3_b32 v48, v48, v52, v53
	v_or3_b32 v48, v48, v54, v55
	s_nop 0
	v_readfirstlane_b32 s0, v48
	s_and_b32 s1, s9, 31
	s_lshl_b32 s1, 1, s1
	s_cmp_lg_u32 s0, 0
	s_cselect_b32 s1, s1, 0
	s_or_b32 s26, s26, s1
	s_add_i32 s9, s9, 1
	s_mov_b32 s0, 0xbfb8aa3b
	v_lshlrev_b32_e32 v56, 16, v32
	v_and_b32_e32 v57, 0xffff0000, v32
	v_lshlrev_b32_e32 v58, 16, v33
	v_and_b32_e32 v59, 0xffff0000, v33
	v_mul_f32_e32 v62, s0, v56
	v_mul_f32_e32 v63, s0, v57
	v_mul_f32_e32 v48, s0, v58
	v_mul_f32_e32 v49, s0, v59
	v_exp_f32_e32 v62, v62
	v_exp_f32_e32 v63, v63
	v_exp_f32_e32 v48, v48
	v_exp_f32_e32 v49, v49
	s_nop 0
	v_add_f32_e32 v62, 1.0, v62
	v_add_f32_e32 v63, 1.0, v63
	v_add_f32_e32 v48, 1.0, v48
	v_add_f32_e32 v49, 1.0, v49
	v_rcp_f32_e32 v62, v62
	v_rcp_f32_e32 v63, v63
	v_rcp_f32_e32 v48, v48
	v_rcp_f32_e32 v49, v49
	s_nop 0
	v_mul_f32_e32 v56, v56, v62
	v_mul_f32_e32 v57, v57, v63
	v_mul_f32_e32 v58, v58, v48
	v_mul_f32_e32 v59, v59, v49
	v_mul_f32_e32 v62, v0, v136
	v_mul_f32_e32 v63, v1, v136
	v_mul_f32_e32 v48, v2, v136
	v_mul_f32_e32 v49, v3, v136
	v_mul_f32_e32 v62, v62, v56
	v_mul_f32_e32 v63, v63, v57
	v_mul_f32_e32 v48, v48, v58
	v_mul_f32_e32 v49, v49, v59
	v_cvt_pk_bf16_f32 v60, v62, v63
	v_cvt_pk_bf16_f32 v61, v48, v49
	global_store_dwordx2 v134, v[60:61], s[30:31] offset:0
	s_nop 0
	v_lshlrev_b32_e32 v56, 16, v34
	v_and_b32_e32 v57, 0xffff0000, v34
	v_lshlrev_b32_e32 v58, 16, v35
	v_and_b32_e32 v59, 0xffff0000, v35
	v_mul_f32_e32 v62, s0, v56
	v_mul_f32_e32 v63, s0, v57
	v_mul_f32_e32 v48, s0, v58
	v_mul_f32_e32 v49, s0, v59
	v_exp_f32_e32 v62, v62
	v_exp_f32_e32 v63, v63
	v_exp_f32_e32 v48, v48
	v_exp_f32_e32 v49, v49
	s_nop 0
	v_add_f32_e32 v62, 1.0, v62
	v_add_f32_e32 v63, 1.0, v63
	v_add_f32_e32 v48, 1.0, v48
	v_add_f32_e32 v49, 1.0, v49
	v_rcp_f32_e32 v62, v62
	v_rcp_f32_e32 v63, v63
	v_rcp_f32_e32 v48, v48
	v_rcp_f32_e32 v49, v49
	s_nop 0
	v_mul_f32_e32 v56, v56, v62
	v_mul_f32_e32 v57, v57, v63
	v_mul_f32_e32 v58, v58, v48
	v_mul_f32_e32 v59, v59, v49
	v_mul_f32_e32 v62, v16, v136
	v_mul_f32_e32 v63, v17, v136
	v_mul_f32_e32 v48, v18, v136
	v_mul_f32_e32 v49, v19, v136
	v_mul_f32_e32 v62, v62, v56
	v_mul_f32_e32 v63, v63, v57
	v_mul_f32_e32 v48, v48, v58
	v_mul_f32_e32 v49, v49, v59
	v_cvt_pk_bf16_f32 v60, v62, v63
	v_cvt_pk_bf16_f32 v61, v48, v49
	global_store_dwordx2 v134, v[60:61], s[30:31] offset:64
	s_nop 0
	v_lshlrev_b32_e32 v56, 16, v36
	v_and_b32_e32 v57, 0xffff0000, v36
	v_lshlrev_b32_e32 v58, 16, v37
	v_and_b32_e32 v59, 0xffff0000, v37
	v_mul_f32_e32 v62, s0, v56
	v_mul_f32_e32 v63, s0, v57
	v_mul_f32_e32 v48, s0, v58
	v_mul_f32_e32 v49, s0, v59
	v_exp_f32_e32 v62, v62
	v_exp_f32_e32 v63, v63
	v_exp_f32_e32 v48, v48
	v_exp_f32_e32 v49, v49
	s_nop 0
	v_add_f32_e32 v62, 1.0, v62
	v_add_f32_e32 v63, 1.0, v63
	v_add_f32_e32 v48, 1.0, v48
	v_add_f32_e32 v49, 1.0, v49
	v_rcp_f32_e32 v62, v62
	v_rcp_f32_e32 v63, v63
	v_rcp_f32_e32 v48, v48
	v_rcp_f32_e32 v49, v49
	s_nop 0
	v_mul_f32_e32 v56, v56, v62
	v_mul_f32_e32 v57, v57, v63
	v_mul_f32_e32 v58, v58, v48
	v_mul_f32_e32 v59, v59, v49
	v_mul_f32_e32 v62, v4, v136
	v_mul_f32_e32 v63, v5, v136
	v_mul_f32_e32 v48, v6, v136
	v_mul_f32_e32 v49, v7, v136
	v_mul_f32_e32 v62, v62, v56
	v_mul_f32_e32 v63, v63, v57
	v_mul_f32_e32 v48, v48, v58
	v_mul_f32_e32 v49, v49, v59
	v_cvt_pk_bf16_f32 v60, v62, v63
	v_cvt_pk_bf16_f32 v61, v48, v49
	global_store_dwordx2 v134, v[60:61], s[30:31] offset:16
	s_nop 0
	v_lshlrev_b32_e32 v56, 16, v38
	v_and_b32_e32 v57, 0xffff0000, v38
	v_lshlrev_b32_e32 v58, 16, v39
	v_and_b32_e32 v59, 0xffff0000, v39
	v_mul_f32_e32 v62, s0, v56
	v_mul_f32_e32 v63, s0, v57
	v_mul_f32_e32 v48, s0, v58
	v_mul_f32_e32 v49, s0, v59
	v_exp_f32_e32 v62, v62
	v_exp_f32_e32 v63, v63
	v_exp_f32_e32 v48, v48
	v_exp_f32_e32 v49, v49
	s_nop 0
	v_add_f32_e32 v62, 1.0, v62
	v_add_f32_e32 v63, 1.0, v63
	v_add_f32_e32 v48, 1.0, v48
	v_add_f32_e32 v49, 1.0, v49
	v_rcp_f32_e32 v62, v62
	v_rcp_f32_e32 v63, v63
	v_rcp_f32_e32 v48, v48
	v_rcp_f32_e32 v49, v49
	s_nop 0
	v_mul_f32_e32 v56, v56, v62
	v_mul_f32_e32 v57, v57, v63
	v_mul_f32_e32 v58, v58, v48
	v_mul_f32_e32 v59, v59, v49
	v_mul_f32_e32 v62, v20, v136
	v_mul_f32_e32 v63, v21, v136
	v_mul_f32_e32 v48, v22, v136
	v_mul_f32_e32 v49, v23, v136
	v_mul_f32_e32 v62, v62, v56
	v_mul_f32_e32 v63, v63, v57
	v_mul_f32_e32 v48, v48, v58
	v_mul_f32_e32 v49, v49, v59
	v_cvt_pk_bf16_f32 v60, v62, v63
	v_cvt_pk_bf16_f32 v61, v48, v49
	global_store_dwordx2 v134, v[60:61], s[30:31] offset:80
	s_nop 0
	v_lshlrev_b32_e32 v56, 16, v40
	v_and_b32_e32 v57, 0xffff0000, v40
	v_lshlrev_b32_e32 v58, 16, v41
	v_and_b32_e32 v59, 0xffff0000, v41
	v_mul_f32_e32 v62, s0, v56
	v_mul_f32_e32 v63, s0, v57
	v_mul_f32_e32 v48, s0, v58
	v_mul_f32_e32 v49, s0, v59
	v_exp_f32_e32 v62, v62
	v_exp_f32_e32 v63, v63
	v_exp_f32_e32 v48, v48
	v_exp_f32_e32 v49, v49
	s_nop 0
	v_add_f32_e32 v62, 1.0, v62
	v_add_f32_e32 v63, 1.0, v63
	v_add_f32_e32 v48, 1.0, v48
	v_add_f32_e32 v49, 1.0, v49
	v_rcp_f32_e32 v62, v62
	v_rcp_f32_e32 v63, v63
	v_rcp_f32_e32 v48, v48
	v_rcp_f32_e32 v49, v49
	s_nop 0
	v_mul_f32_e32 v56, v56, v62
	v_mul_f32_e32 v57, v57, v63
	v_mul_f32_e32 v58, v58, v48
	v_mul_f32_e32 v59, v59, v49
	v_mul_f32_e32 v62, v8, v136
	v_mul_f32_e32 v63, v9, v136
	v_mul_f32_e32 v48, v10, v136
	v_mul_f32_e32 v49, v11, v136
	v_mul_f32_e32 v62, v62, v56
	v_mul_f32_e32 v63, v63, v57
	v_mul_f32_e32 v48, v48, v58
	v_mul_f32_e32 v49, v49, v59
	v_cvt_pk_bf16_f32 v60, v62, v63
	v_cvt_pk_bf16_f32 v61, v48, v49
	global_store_dwordx2 v134, v[60:61], s[30:31] offset:32
	s_nop 0
	v_lshlrev_b32_e32 v56, 16, v42
	v_and_b32_e32 v57, 0xffff0000, v42
	v_lshlrev_b32_e32 v58, 16, v43
	v_and_b32_e32 v59, 0xffff0000, v43
	v_mul_f32_e32 v62, s0, v56
	v_mul_f32_e32 v63, s0, v57
	v_mul_f32_e32 v48, s0, v58
	v_mul_f32_e32 v49, s0, v59
	v_exp_f32_e32 v62, v62
	v_exp_f32_e32 v63, v63
	v_exp_f32_e32 v48, v48
	v_exp_f32_e32 v49, v49
	s_nop 0
	v_add_f32_e32 v62, 1.0, v62
	v_add_f32_e32 v63, 1.0, v63
	v_add_f32_e32 v48, 1.0, v48
	v_add_f32_e32 v49, 1.0, v49
	v_rcp_f32_e32 v62, v62
	v_rcp_f32_e32 v63, v63
	v_rcp_f32_e32 v48, v48
	v_rcp_f32_e32 v49, v49
	s_nop 0
	v_mul_f32_e32 v56, v56, v62
	v_mul_f32_e32 v57, v57, v63
	v_mul_f32_e32 v58, v58, v48
	v_mul_f32_e32 v59, v59, v49
	v_mul_f32_e32 v62, v24, v136
	v_mul_f32_e32 v63, v25, v136
	v_mul_f32_e32 v48, v26, v136
	v_mul_f32_e32 v49, v27, v136
	v_mul_f32_e32 v62, v62, v56
	v_mul_f32_e32 v63, v63, v57
	v_mul_f32_e32 v48, v48, v58
	v_mul_f32_e32 v49, v49, v59
	v_cvt_pk_bf16_f32 v60, v62, v63
	v_cvt_pk_bf16_f32 v61, v48, v49
	global_store_dwordx2 v134, v[60:61], s[30:31] offset:96
	s_nop 0
	v_lshlrev_b32_e32 v56, 16, v44
	v_and_b32_e32 v57, 0xffff0000, v44
	v_lshlrev_b32_e32 v58, 16, v45
	v_and_b32_e32 v59, 0xffff0000, v45
	v_mul_f32_e32 v62, s0, v56
	v_mul_f32_e32 v63, s0, v57
	v_mul_f32_e32 v48, s0, v58
	v_mul_f32_e32 v49, s0, v59
	v_exp_f32_e32 v62, v62
	v_exp_f32_e32 v63, v63
	v_exp_f32_e32 v48, v48
	v_exp_f32_e32 v49, v49
	s_nop 0
	v_add_f32_e32 v62, 1.0, v62
	v_add_f32_e32 v63, 1.0, v63
	v_add_f32_e32 v48, 1.0, v48
	v_add_f32_e32 v49, 1.0, v49
	v_rcp_f32_e32 v62, v62
	v_rcp_f32_e32 v63, v63
	v_rcp_f32_e32 v48, v48
	v_rcp_f32_e32 v49, v49
	s_nop 0
	v_mul_f32_e32 v56, v56, v62
	v_mul_f32_e32 v57, v57, v63
	v_mul_f32_e32 v58, v58, v48
	v_mul_f32_e32 v59, v59, v49
	v_mul_f32_e32 v62, v12, v136
	v_mul_f32_e32 v63, v13, v136
	v_mul_f32_e32 v48, v14, v136
	v_mul_f32_e32 v49, v15, v136
	v_mul_f32_e32 v62, v62, v56
	v_mul_f32_e32 v63, v63, v57
	v_mul_f32_e32 v48, v48, v58
	v_mul_f32_e32 v49, v49, v59
	v_cvt_pk_bf16_f32 v60, v62, v63
	v_cvt_pk_bf16_f32 v61, v48, v49
	global_store_dwordx2 v134, v[60:61], s[30:31] offset:48
	s_nop 0
	v_lshlrev_b32_e32 v56, 16, v46
	v_and_b32_e32 v57, 0xffff0000, v46
	v_lshlrev_b32_e32 v58, 16, v47
	v_and_b32_e32 v59, 0xffff0000, v47
	v_mul_f32_e32 v62, s0, v56
	v_mul_f32_e32 v63, s0, v57
	v_mul_f32_e32 v48, s0, v58
	v_mul_f32_e32 v49, s0, v59
	v_exp_f32_e32 v62, v62
	v_exp_f32_e32 v63, v63
	v_exp_f32_e32 v48, v48
	v_exp_f32_e32 v49, v49
	s_nop 0
	v_add_f32_e32 v62, 1.0, v62
	v_add_f32_e32 v63, 1.0, v63
	v_add_f32_e32 v48, 1.0, v48
	v_add_f32_e32 v49, 1.0, v49
	v_rcp_f32_e32 v62, v62
	v_rcp_f32_e32 v63, v63
	v_rcp_f32_e32 v48, v48
	v_rcp_f32_e32 v49, v49
	s_nop 0
	v_mul_f32_e32 v56, v56, v62
	v_mul_f32_e32 v57, v57, v63
	v_mul_f32_e32 v58, v58, v48
	v_mul_f32_e32 v59, v59, v49
	v_mul_f32_e32 v62, v28, v136
	v_mul_f32_e32 v63, v29, v136
	v_mul_f32_e32 v48, v30, v136
	v_mul_f32_e32 v49, v31, v136
	v_mul_f32_e32 v62, v62, v56
	v_mul_f32_e32 v63, v63, v57
	v_mul_f32_e32 v48, v48, v58
	v_mul_f32_e32 v49, v49, v59
	v_cvt_pk_bf16_f32 v60, v62, v63
	v_cvt_pk_bf16_f32 v61, v48, v49
	global_store_dwordx2 v134, v[60:61], s[30:31] offset:112
	s_nop 0
	s_cmp_eq_u32 s101, 1
	s_cbranch_scc1 .Lat_m_pref
	s_cmp_eq_u32 s101, 2
	s_cbranch_scc1 .Lat_g_pref
	s_branch .Lat_done
.Lat_g_pref:
	v_and_b32_e32 v32, 31, v143
	v_bfe_u32 v33, v143, 5, 1
	v_mul_u32_u24_e32 v237, 144, v32
	v_lshl_add_u32 v237, v33, 4, v237
	v_mov_b32_e32 v36, v143
	v_lshrrev_b32_e32 v37, 3, v36
	v_and_b32_e32 v38, 7, v36
	v_mul_u32_u24_e32 v37, 144, v37
	v_lshl_add_u32 v179, v38, 4, v37
	v_add_u32_e32 v36, 512, v143
	v_lshrrev_b32_e32 v37, 3, v36
	v_and_b32_e32 v38, 7, v36
	v_mul_u32_u24_e32 v37, 144, v37
	v_lshl_add_u32 v181, v38, 4, v37
	s_mov_b32 s64, 0
	s_movk_i32 s65, 18432
	s_mov_b32 s68, 36864
	s_mov_b32 s69, 112640
	s_mov_b32 s70, 79872
	s_mov_b32 s71, 96256
	v_mov_b32_e32 v130, 0
	v_mov_b32_e32 v131, 0
	v_mov_b32_e32 v0, 0
	v_mov_b32_e32 v1, 0
	v_mov_b32_e32 v2, 0
	v_mov_b32_e32 v3, 0
	v_mov_b32_e32 v4, 0
	v_mov_b32_e32 v5, 0
	v_mov_b32_e32 v6, 0
	v_mov_b32_e32 v7, 0
	v_mov_b32_e32 v8, 0
	v_mov_b32_e32 v9, 0
	v_mov_b32_e32 v10, 0
	v_mov_b32_e32 v11, 0
	v_mov_b32_e32 v12, 0
	v_mov_b32_e32 v13, 0
	v_mov_b32_e32 v14, 0
	v_mov_b32_e32 v15, 0
	v_mov_b32_e32 v16, 0
	v_mov_b32_e32 v17, 0
	v_mov_b32_e32 v18, 0
	v_mov_b32_e32 v19, 0
	v_mov_b32_e32 v20, 0
	v_mov_b32_e32 v21, 0
	v_mov_b32_e32 v22, 0
	v_mov_b32_e32 v23, 0
	v_mov_b32_e32 v24, 0
	v_mov_b32_e32 v25, 0
	v_mov_b32_e32 v26, 0
	v_mov_b32_e32 v27, 0
	v_mov_b32_e32 v28, 0
	v_mov_b32_e32 v29, 0
	v_mov_b32_e32 v30, 0
	v_mov_b32_e32 v31, 0
	s_waitcnt vmcnt(10)
	ds_write_b128 v179, v[208:211]
	ds_write_b128 v181, v[212:215]
	v_add_u32_e32 v128, 79872, v183
	ds_write_b128 v128, v[220:223]
	ds_write_b128 v128, v[224:227] offset:8192
	global_load_dwordx4 v[208:211], v232, s[16:17]
	global_load_dwordx4 v[212:215], v239, s[16:17]
	global_load_dwordx4 v[220:223], v232, s[22:23]
	global_load_dwordx4 v[224:227], v239, s[22:23]
	s_add_u32 s16, s16, 16384
	s_addc_u32 s17, s17, 0
	s_add_u32 s22, s22, 16384
	s_addc_u32 s23, s23, 0
	s_waitcnt vmcnt(12)
	v_add_u32_e32 v128, 18432, v179
	ds_write_b128 v128, v[144:147]
	v_add_u32_e32 v128, 18432, v181
	ds_write_b128 v128, v[148:151]
	v_add_u32_e32 v140, s64, v237
	s_waitcnt lgkmcnt(0)
	s_barrier
	s_branch .Lat_g_body
.Lat_g_first:
	v_and_b32_e32 v32, 31, v143
	v_bfe_u32 v33, v143, 5, 1
	v_mul_u32_u24_e32 v237, 144, v32
	v_lshl_add_u32 v237, v33, 4, v237
	v_mov_b32_e32 v36, v143
	v_lshrrev_b32_e32 v37, 3, v36
	v_and_b32_e32 v38, 7, v36
	v_mul_u32_u24_e32 v37, 144, v37
	v_lshl_add_u32 v179, v38, 4, v37
	v_add_u32_e32 v36, 512, v143
	v_lshrrev_b32_e32 v37, 3, v36
	v_and_b32_e32 v38, 7, v36
	v_mul_u32_u24_e32 v37, 144, v37
	v_lshl_add_u32 v181, v38, 4, v37
	s_mov_b32 s64, 0
	s_movk_i32 s65, 18432
	s_mov_b32 s68, 36864
	s_mov_b32 s69, 112640
	s_mov_b32 s70, 79872
	s_mov_b32 s71, 96256
	v_mov_b32_e32 v130, 0
	v_mov_b32_e32 v131, 0
	v_mov_b32_e32 v0, 0
	v_mov_b32_e32 v1, 0
	v_mov_b32_e32 v2, 0
	v_mov_b32_e32 v3, 0
	v_mov_b32_e32 v4, 0
	v_mov_b32_e32 v5, 0
	v_mov_b32_e32 v6, 0
	v_mov_b32_e32 v7, 0
	v_mov_b32_e32 v8, 0
	v_mov_b32_e32 v9, 0
	v_mov_b32_e32 v10, 0
	v_mov_b32_e32 v11, 0
	v_mov_b32_e32 v12, 0
	v_mov_b32_e32 v13, 0
	v_mov_b32_e32 v14, 0
	v_mov_b32_e32 v15, 0
	v_mov_b32_e32 v16, 0
	v_mov_b32_e32 v17, 0
	v_mov_b32_e32 v18, 0
	v_mov_b32_e32 v19, 0
	v_mov_b32_e32 v20, 0
	v_mov_b32_e32 v21, 0
	v_mov_b32_e32 v22, 0
	v_mov_b32_e32 v23, 0
	v_mov_b32_e32 v24, 0
	v_mov_b32_e32 v25, 0
	v_mov_b32_e32 v26, 0
	v_mov_b32_e32 v27, 0
	v_mov_b32_e32 v28, 0
	v_mov_b32_e32 v29, 0
	v_mov_b32_e32 v30, 0
	v_mov_b32_e32 v31, 0
	s_waitcnt vmcnt(2)
	ds_write_b128 v179, v[208:211]
	ds_write_b128 v181, v[212:215]
	v_add_u32_e32 v128, 79872, v183
	ds_write_b128 v128, v[220:223]
	ds_write_b128 v128, v[224:227] offset:8192
	global_load_dwordx4 v[208:211], v232, s[16:17]
	global_load_dwordx4 v[212:215], v239, s[16:17]
	global_load_dwordx4 v[220:223], v232, s[22:23]
	global_load_dwordx4 v[224:227], v239, s[22:23]
	s_add_u32 s16, s16, 16384
	s_addc_u32 s17, s17, 0
	s_add_u32 s22, s22, 16384
	s_addc_u32 s23, s23, 0
	s_waitcnt vmcnt(4)
	v_add_u32_e32 v128, 18432, v179
	ds_write_b128 v128, v[144:147]
	v_add_u32_e32 v128, 18432, v181
	ds_write_b128 v128, v[148:151]
	v_add_u32_e32 v140, s64, v237
	s_waitcnt lgkmcnt(0)
	s_barrier

.Lat_g_last:
	v_add_u32_e32 v140, s64, v237
	v_add_u32_e32 v141, s65, v237
	v_add_u32_e32 v176, s69, v238
	v_add_u32_e32 v177, s70, v238
	s_waitcnt lgkmcnt(5)
	v_mfma_f32_32x32x16_bf16 v[64:79], v[144:147], v[184:187], 0
	ds_read_b128 v[168:171], v140 offset:13888
	v_exp_f32_e32 v32, v32
	v_exp_f32_e32 v33, v33
	v_add_f32_e32 v130, v130, v32
	v_add_f32_e32 v131, v131, v33
	v_cvt_pk_bf16_f32 v96, v32, v33
	s_waitcnt lgkmcnt(5)
	v_mfma_f32_32x32x16_bf16 v[64:79], v[148:151], v[188:191], v[64:79]
	ds_read_b128 v[172:175], v140 offset:13920
	v_exp_f32_e32 v34, v34
	v_exp_f32_e32 v35, v35
	v_add_f32_e32 v130, v130, v34
	v_add_f32_e32 v131, v131, v35
	v_cvt_pk_bf16_f32 v97, v34, v35
	s_waitcnt lgkmcnt(5)
	v_mfma_f32_32x32x16_bf16 v[64:79], v[152:155], v[192:195], v[64:79]
	ds_read_b64_tr_b16 v[144:145], v176 offset:8192
	ds_read_b64_tr_b16 v[146:147], v176 offset:9216
	v_exp_f32_e32 v36, v36
	v_exp_f32_e32 v37, v37
	v_add_f32_e32 v130, v130, v36
	v_add_f32_e32 v131, v131, v37
	v_cvt_pk_bf16_f32 v98, v36, v37
	s_waitcnt lgkmcnt(6)
	v_mfma_f32_32x32x16_bf16 v[64:79], v[156:159], v[196:199], v[64:79]
	ds_read_b64_tr_b16 v[148:149], v176 offset:8704
	ds_read_b64_tr_b16 v[150:151], v176 offset:9728
	v_exp_f32_e32 v38, v38
	v_exp_f32_e32 v39, v39
	v_add_f32_e32 v130, v130, v38
	v_add_f32_e32 v131, v131, v39
	v_cvt_pk_bf16_f32 v99, v38, v39
	s_waitcnt lgkmcnt(7)
	v_mfma_f32_32x32x16_bf16 v[80:95], v[160:163], v[184:187], 0
	ds_read_b64_tr_b16 v[152:153], v176 offset:10240
	ds_read_b64_tr_b16 v[154:155], v176 offset:11264
	v_exp_f32_e32 v40, v40
	v_exp_f32_e32 v41, v41
	v_add_f32_e32 v130, v130, v40
	v_add_f32_e32 v131, v131, v41
	v_cvt_pk_bf16_f32 v100, v40, v41
	s_waitcnt lgkmcnt(8)
	v_mfma_f32_32x32x16_bf16 v[80:95], v[164:167], v[188:191], v[80:95]
	ds_read_b64_tr_b16 v[156:157], v176 offset:10752
	ds_read_b64_tr_b16 v[158:159], v176 offset:11776
	v_exp_f32_e32 v42, v42
	v_exp_f32_e32 v43, v43
	v_add_f32_e32 v130, v130, v42
	v_add_f32_e32 v131, v131, v43
	v_cvt_pk_bf16_f32 v101, v42, v43
	s_waitcnt lgkmcnt(9)
	v_mfma_f32_32x32x16_bf16 v[80:95], v[168:171], v[192:195], v[80:95]
	ds_read_b64_tr_b16 v[160:161], v176 offset:12288
	ds_read_b64_tr_b16 v[162:163], v176 offset:13312
	v_exp_f32_e32 v44, v44
	v_exp_f32_e32 v45, v45
	v_add_f32_e32 v130, v130, v44
	v_add_f32_e32 v131, v131, v45
	v_cvt_pk_bf16_f32 v102, v44, v45
	s_waitcnt lgkmcnt(10)
	v_mfma_f32_32x32x16_bf16 v[80:95], v[172:175], v[196:199], v[80:95]
	ds_read_b64_tr_b16 v[164:165], v176 offset:12800
	ds_read_b64_tr_b16 v[166:167], v176 offset:13824
	v_exp_f32_e32 v46, v46
	v_exp_f32_e32 v47, v47
	v_add_f32_e32 v130, v130, v46
	v_add_f32_e32 v131, v131, v47
	v_cvt_pk_bf16_f32 v103, v46, v47
	s_waitcnt lgkmcnt(10)
	v_mfma_f32_32x32x16_bf16 v[0:15], v[144:147], v[112:115], v[0:15]
	ds_read_b64_tr_b16 v[168:169], v176 offset:14336
	ds_read_b64_tr_b16 v[170:171], v176 offset:15360
	v_exp_f32_e32 v48, v48
	v_exp_f32_e32 v49, v49
	v_add_f32_e32 v130, v130, v48
	v_add_f32_e32 v131, v131, v49
	v_cvt_pk_bf16_f32 v104, v48, v49
	s_waitcnt lgkmcnt(10)
	v_mfma_f32_32x32x16_bf16 v[16:31], v[148:151], v[112:115], v[16:31]
	ds_read_b64_tr_b16 v[172:173], v176 offset:14848
	ds_read_b64_tr_b16 v[174:175], v176 offset:15872
	v_exp_f32_e32 v50, v50
	v_exp_f32_e32 v51, v51
	v_add_f32_e32 v130, v130, v50
	v_add_f32_e32 v131, v131, v51
	v_cvt_pk_bf16_f32 v105, v50, v51
	s_waitcnt lgkmcnt(10)
	v_mfma_f32_32x32x16_bf16 v[0:15], v[152:155], v[116:119], v[0:15]
	ds_read_b64_tr_b16 v[144:145], v177 offset:0
	ds_read_b64_tr_b16 v[146:147], v177 offset:1024
	v_exp_f32_e32 v52, v52
	v_exp_f32_e32 v53, v53
	v_add_f32_e32 v130, v130, v52
	v_add_f32_e32 v131, v131, v53
	v_cvt_pk_bf16_f32 v106, v52, v53
	s_waitcnt lgkmcnt(10)
	v_mfma_f32_32x32x16_bf16 v[16:31], v[156:159], v[116:119], v[16:31]
	ds_read_b64_tr_b16 v[148:149], v177 offset:512
	ds_read_b64_tr_b16 v[150:151], v177 offset:1536
	v_exp_f32_e32 v54, v54
	v_exp_f32_e32 v55, v55
	v_add_f32_e32 v130, v130, v54
	v_add_f32_e32 v131, v131, v55
	v_cvt_pk_bf16_f32 v107, v54, v55
	s_waitcnt lgkmcnt(10)
	v_mfma_f32_32x32x16_bf16 v[0:15], v[160:163], v[120:123], v[0:15]
	ds_read_b64_tr_b16 v[152:153], v177 offset:2048
	ds_read_b64_tr_b16 v[154:155], v177 offset:3072
	v_exp_f32_e32 v56, v56
	v_exp_f32_e32 v57, v57
	v_add_f32_e32 v130, v130, v56
	v_add_f32_e32 v131, v131, v57
	v_cvt_pk_bf16_f32 v108, v56, v57
	s_waitcnt lgkmcnt(10)
	v_mfma_f32_32x32x16_bf16 v[16:31], v[164:167], v[120:123], v[16:31]
	ds_read_b64_tr_b16 v[156:157], v177 offset:2560
	ds_read_b64_tr_b16 v[158:159], v177 offset:3584
	v_exp_f32_e32 v58, v58
	v_exp_f32_e32 v59, v59
	v_add_f32_e32 v130, v130, v58
	v_add_f32_e32 v131, v131, v59
	v_cvt_pk_bf16_f32 v109, v58, v59
	s_waitcnt lgkmcnt(10)
	v_mfma_f32_32x32x16_bf16 v[0:15], v[168:171], v[124:127], v[0:15]
	ds_read_b64_tr_b16 v[160:161], v177 offset:4096
	ds_read_b64_tr_b16 v[162:163], v177 offset:5120
	v_exp_f32_e32 v60, v60
	v_exp_f32_e32 v61, v61
	v_add_f32_e32 v130, v130, v60
	v_add_f32_e32 v131, v131, v61
	v_cvt_pk_bf16_f32 v110, v60, v61
	s_waitcnt lgkmcnt(10)
	v_mfma_f32_32x32x16_bf16 v[16:31], v[172:175], v[124:127], v[16:31]
	ds_read_b64_tr_b16 v[164:165], v177 offset:4608
	ds_read_b64_tr_b16 v[166:167], v177 offset:5632
	v_exp_f32_e32 v62, v62
	v_exp_f32_e32 v63, v63
	v_add_f32_e32 v130, v130, v62
	v_add_f32_e32 v131, v131, v63
	v_cvt_pk_bf16_f32 v111, v62, v63
	s_waitcnt lgkmcnt(10)
	v_mfma_f32_32x32x16_bf16 v[0:15], v[144:147], v[96:99], v[0:15]
	ds_read_b64_tr_b16 v[168:169], v177 offset:6144
	ds_read_b64_tr_b16 v[170:171], v177 offset:7168
	v_exp_f32_e32 v64, v64
	v_exp_f32_e32 v65, v65
	v_add_f32_e32 v130, v130, v64
	v_add_f32_e32 v131, v131, v65
	v_cvt_pk_bf16_f32 v112, v64, v65
	v_exp_f32_e32 v66, v66
	v_exp_f32_e32 v67, v67
	v_add_f32_e32 v130, v130, v66
	v_add_f32_e32 v131, v131, v67
	v_cvt_pk_bf16_f32 v113, v66, v67
	global_load_dwordx2 v[32:33], v133, s[12:13] offset:0
	s_waitcnt lgkmcnt(10)
	v_mfma_f32_32x32x16_bf16 v[16:31], v[148:151], v[96:99], v[16:31]
	ds_read_b64_tr_b16 v[172:173], v177 offset:6656
	ds_read_b64_tr_b16 v[174:175], v177 offset:7680
	v_exp_f32_e32 v68, v68
	v_exp_f32_e32 v69, v69
	v_add_f32_e32 v130, v130, v68
	v_add_f32_e32 v131, v131, v69
	v_cvt_pk_bf16_f32 v114, v68, v69
	v_exp_f32_e32 v70, v70
	v_exp_f32_e32 v71, v71
	v_add_f32_e32 v130, v130, v70
	v_add_f32_e32 v131, v131, v71
	v_cvt_pk_bf16_f32 v115, v70, v71
	global_load_dwordx2 v[34:35], v133, s[12:13] offset:64
	s_waitcnt lgkmcnt(10)
	v_mfma_f32_32x32x16_bf16 v[0:15], v[152:155], v[100:103], v[0:15]
	v_exp_f32_e32 v72, v72
	v_exp_f32_e32 v73, v73
	v_add_f32_e32 v130, v130, v72
	v_add_f32_e32 v131, v131, v73
	v_cvt_pk_bf16_f32 v116, v72, v73
	v_exp_f32_e32 v74, v74
	v_exp_f32_e32 v75, v75
	v_add_f32_e32 v130, v130, v74
	v_add_f32_e32 v131, v131, v75
	v_cvt_pk_bf16_f32 v117, v74, v75
	global_load_dwordx2 v[36:37], v133, s[12:13] offset:16
	s_waitcnt lgkmcnt(8)
	v_mfma_f32_32x32x16_bf16 v[16:31], v[156:159], v[100:103], v[16:31]
	v_exp_f32_e32 v76, v76
	v_exp_f32_e32 v77, v77
	v_add_f32_e32 v130, v130, v76
	v_add_f32_e32 v131, v131, v77
	v_cvt_pk_bf16_f32 v118, v76, v77
	v_exp_f32_e32 v78, v78
	v_exp_f32_e32 v79, v79
	v_add_f32_e32 v130, v130, v78
	v_add_f32_e32 v131, v131, v79
	v_cvt_pk_bf16_f32 v119, v78, v79
	global_load_dwordx2 v[38:39], v133, s[12:13] offset:80
	s_waitcnt lgkmcnt(6)
	v_mfma_f32_32x32x16_bf16 v[0:15], v[160:163], v[104:107], v[0:15]
	v_exp_f32_e32 v80, v80
	v_exp_f32_e32 v81, v81
	v_add_f32_e32 v130, v130, v80
	v_add_f32_e32 v131, v131, v81
	v_cvt_pk_bf16_f32 v120, v80, v81
	v_exp_f32_e32 v82, v82
	v_exp_f32_e32 v83, v83
	v_add_f32_e32 v130, v130, v82
	v_add_f32_e32 v131, v131, v83
	v_cvt_pk_bf16_f32 v121, v82, v83
	global_load_dwordx2 v[40:41], v133, s[12:13] offset:32
	s_waitcnt lgkmcnt(4)
	v_mfma_f32_32x32x16_bf16 v[16:31], v[164:167], v[104:107], v[16:31]
	v_exp_f32_e32 v84, v84
	v_exp_f32_e32 v85, v85
	v_add_f32_e32 v130, v130, v84
	v_add_f32_e32 v131, v131, v85
	v_cvt_pk_bf16_f32 v122, v84, v85
	v_exp_f32_e32 v86, v86
	v_exp_f32_e32 v87, v87
	v_add_f32_e32 v130, v130, v86
	v_add_f32_e32 v131, v131, v87
	v_cvt_pk_bf16_f32 v123, v86, v87
	global_load_dwordx2 v[42:43], v133, s[12:13] offset:96
	s_waitcnt lgkmcnt(2)
	v_mfma_f32_32x32x16_bf16 v[0:15], v[168:171], v[108:111], v[0:15]
	v_exp_f32_e32 v88, v88
	v_exp_f32_e32 v89, v89
	v_add_f32_e32 v130, v130, v88
	v_add_f32_e32 v131, v131, v89
	v_cvt_pk_bf16_f32 v124, v88, v89
	v_exp_f32_e32 v90, v90
	v_exp_f32_e32 v91, v91
	v_add_f32_e32 v130, v130, v90
	v_add_f32_e32 v131, v131, v91
	v_cvt_pk_bf16_f32 v125, v90, v91
	global_load_dwordx2 v[44:45], v133, s[12:13] offset:48
	s_waitcnt lgkmcnt(0)
	v_mfma_f32_32x32x16_bf16 v[16:31], v[172:175], v[108:111], v[16:31]
	v_exp_f32_e32 v92, v92
	v_exp_f32_e32 v93, v93
	v_add_f32_e32 v130, v130, v92
	v_add_f32_e32 v131, v131, v93
	v_cvt_pk_bf16_f32 v126, v92, v93
	v_exp_f32_e32 v94, v94
	v_exp_f32_e32 v95, v95
	v_add_f32_e32 v130, v130, v94
	v_add_f32_e32 v131, v131, v95
	v_cvt_pk_bf16_f32 v127, v94, v95
	global_load_dwordx2 v[46:47], v133, s[12:13] offset:112
	v_add_u32_e32 v176, s70, v238
	ds_read_b64_tr_b16 v[144:145], v176 offset:8192
	ds_read_b64_tr_b16 v[146:147], v176 offset:9216
	ds_read_b64_tr_b16 v[148:149], v176 offset:8704
	ds_read_b64_tr_b16 v[150:151], v176 offset:9728
	ds_read_b64_tr_b16 v[152:153], v176 offset:10240
	ds_read_b64_tr_b16 v[154:155], v176 offset:11264
	ds_read_b64_tr_b16 v[156:157], v176 offset:10752
	ds_read_b64_tr_b16 v[158:159], v176 offset:11776
	ds_read_b64_tr_b16 v[160:161], v176 offset:12288
	ds_read_b64_tr_b16 v[162:163], v176 offset:13312
	ds_read_b64_tr_b16 v[164:165], v176 offset:12800
	ds_read_b64_tr_b16 v[166:167], v176 offset:13824
	s_waitcnt lgkmcnt(10)
	v_mfma_f32_32x32x16_bf16 v[0:15], v[144:147], v[112:115], v[0:15]
	ds_read_b64_tr_b16 v[168:169], v176 offset:14336
	ds_read_b64_tr_b16 v[170:171], v176 offset:15360
	s_waitcnt lgkmcnt(10)
	v_mfma_f32_32x32x16_bf16 v[16:31], v[148:151], v[112:115], v[16:31]
	ds_read_b64_tr_b16 v[172:173], v176 offset:14848
	ds_read_b64_tr_b16 v[174:175], v176 offset:15872
	s_waitcnt lgkmcnt(10)
	v_mfma_f32_32x32x16_bf16 v[0:15], v[152:155], v[116:119], v[0:15]
	s_waitcnt lgkmcnt(8)
	v_mfma_f32_32x32x16_bf16 v[16:31], v[156:159], v[116:119], v[16:31]
	s_waitcnt lgkmcnt(6)
	v_mfma_f32_32x32x16_bf16 v[0:15], v[160:163], v[120:123], v[0:15]
	s_waitcnt lgkmcnt(4)
	v_mfma_f32_32x32x16_bf16 v[16:31], v[164:167], v[120:123], v[16:31]
	s_waitcnt lgkmcnt(2)
	v_mfma_f32_32x32x16_bf16 v[0:15], v[168:171], v[124:127], v[0:15]
	s_waitcnt lgkmcnt(0)
	v_mfma_f32_32x32x16_bf16 v[16:31], v[172:175], v[124:127], v[16:31]
	s_waitcnt vmcnt(0)
	s_mov_b64 s[30:31], s[14:15]
	s_add_i32 s4, s4, s5
	s_mov_b32 s101, 0
	s_cmp_ge_i32 s4, s7
	s_cbranch_scc1 .Lat_dg_end
	s_cmp_ge_i32 s4, s6
	s_cbranch_scc1 .Lat_dg_ctx
	s_mul_i32 s0, s8, s6
	s_add_i32 s0, s0, s4
	s_mul_hi_u32 s1, s0, 0xaaaaaaab
	s_lshr_b32 s1, s1, 7
	s_mul_i32 s32, s1, 192
	s_sub_i32 s32, s0, s32
	s_lshr_b32 s56, s32, 4
	s_and_b32 s32, s32, 15
	s_lshl_b32 s76, s32, 8
	s_lshl_b32 s77, s1, 12
	s_add_i32 s77, s77, s76
	s_mov_b32 s78, 0
	s_mov_b32 s27, 32
	s_branch .Lat_dg_ptrs
